# bundle: mixer load de-serialisation (u tile, pscale, conv gate) + XCD release before leader invalidate + setprio around attention MFMA clusters
# speedup vs baseline: 1.0081x; 1.0081x over previous
.Lgsx_1255:
	s_or_b64 exec, exec, s[6:7]
	s_mov_b64 s[0:1], exec
	v_mbcnt_lo_u32_b32 v0, s0, 0
	v_mbcnt_hi_u32_b32 v0, s1, v0
	v_cmp_eq_u32_e32 vcc, 0, v0
	s_and_saveexec_b64 s[6:7], vcc
	s_cbranch_execz .Lgsx_1257
	s_bcnt1_i32_b64 s0, s[0:1]
	v_mov_b32_e32 v0, s0
	global_atomic_add v253, v0, s[2:3] offset:1024
.Lgsx_1257:
	s_or_b64 exec, exec, s[6:7]
	buffer_inv sc1
	s_waitcnt vmcnt(0)

.LBB0_348:
	s_and_b32 s29, s79, 3
	s_ashr_i32 s26, s79, 7
	s_lshl_b32 s0, s79, 5
	s_and_b32 s28, s0, 0xf80
	s_ashr_i32 s27, s26, 31
	s_lshl_b32 s84, s29, 9
	s_lshl_b64 s[58:59], s[26:27], 12
	v_lshl_add_u64 v[4:5], v[68:69], 0, s[84:85]
	s_add_i32 s24, s28, -15
	s_lshl_b32 s64, s29, 8
	s_mov_b64 s[2:3], exec
	s_and_b64 exec, s[2:3], s[6:7]
	v_add_u32_e32 v188, s24, v64
	v_cmp_lt_i32_e32 vcc, -1, v188
	v_mov_b32_e32 v140, 0
	v_mov_b32_e32 v141, 0
	v_mov_b32_e32 v142, 0
	v_mov_b32_e32 v143, 0
	v_lshl_add_u64 v[176:177], s[58:59], 0, v[188:189]
	v_lshlrev_b64 v[176:177], 13, v[176:177]
	v_lshl_add_u64 v[176:177], v[4:5], 0, v[176:177]
	s_and_b64 exec, exec, vcc
	global_load_dwordx4 v[140:143], v[176:177], off
	s_and_b64 exec, s[2:3], s[8:9]
	v_add_u32_e32 v188, s24, v88
	v_cmp_lt_i32_e32 vcc, -1, v188
	v_mov_b32_e32 v144, 0
	v_mov_b32_e32 v145, 0
	v_mov_b32_e32 v146, 0
	v_mov_b32_e32 v147, 0
	v_lshl_add_u64 v[176:177], s[58:59], 0, v[188:189]
	v_lshlrev_b64 v[176:177], 13, v[176:177]
	v_lshl_add_u64 v[176:177], v[4:5], 0, v[176:177]
	s_and_b64 exec, exec, vcc
	global_load_dwordx4 v[144:147], v[176:177], off
	s_and_b64 exec, s[2:3], s[10:11]
	v_add_u32_e32 v188, s24, v90
	v_cmp_lt_i32_e32 vcc, -1, v188
	v_mov_b32_e32 v148, 0
	v_mov_b32_e32 v149, 0
	v_mov_b32_e32 v150, 0
	v_mov_b32_e32 v151, 0
	v_lshl_add_u64 v[176:177], s[58:59], 0, v[188:189]
	v_lshlrev_b64 v[176:177], 13, v[176:177]
	v_lshl_add_u64 v[176:177], v[4:5], 0, v[176:177]
	s_and_b64 exec, exec, vcc
	global_load_dwordx4 v[148:151], v[176:177], off
	s_and_b64 exec, s[2:3], s[12:13]
	v_add_u32_e32 v188, s24, v91
	v_cmp_lt_i32_e32 vcc, -1, v188
	v_mov_b32_e32 v152, 0
	v_mov_b32_e32 v153, 0
	v_mov_b32_e32 v154, 0
	v_mov_b32_e32 v155, 0
	v_lshl_add_u64 v[176:177], s[58:59], 0, v[188:189]
	v_lshlrev_b64 v[176:177], 13, v[176:177]
	v_lshl_add_u64 v[176:177], v[4:5], 0, v[176:177]
	s_and_b64 exec, exec, vcc
	global_load_dwordx4 v[152:155], v[176:177], off
	s_and_b64 exec, s[2:3], s[14:15]
	v_add_u32_e32 v188, s24, v92
	v_cmp_lt_i32_e32 vcc, -1, v188
	v_mov_b32_e32 v156, 0
	v_mov_b32_e32 v157, 0
	v_mov_b32_e32 v158, 0
	v_mov_b32_e32 v159, 0
	v_lshl_add_u64 v[176:177], s[58:59], 0, v[188:189]
	v_lshlrev_b64 v[176:177], 13, v[176:177]
	v_lshl_add_u64 v[176:177], v[4:5], 0, v[176:177]
	s_and_b64 exec, exec, vcc
	global_load_dwordx4 v[156:159], v[176:177], off
	s_and_b64 exec, s[2:3], s[16:17]
	v_add_u32_e32 v188, s24, v93
	v_cmp_lt_i32_e32 vcc, -1, v188
	v_mov_b32_e32 v160, 0
	v_mov_b32_e32 v161, 0
	v_mov_b32_e32 v162, 0
	v_mov_b32_e32 v163, 0
	v_lshl_add_u64 v[176:177], s[58:59], 0, v[188:189]
	v_lshlrev_b64 v[176:177], 13, v[176:177]
	v_lshl_add_u64 v[176:177], v[4:5], 0, v[176:177]
	s_and_b64 exec, exec, vcc
	global_load_dwordx4 v[160:163], v[176:177], off
	s_and_b64 exec, s[2:3], s[18:19]
	v_add_u32_e32 v188, s24, v94
	v_cmp_lt_i32_e32 vcc, -1, v188
	v_mov_b32_e32 v164, 0
	v_mov_b32_e32 v165, 0
	v_mov_b32_e32 v166, 0
	v_mov_b32_e32 v167, 0
	v_lshl_add_u64 v[176:177], s[58:59], 0, v[188:189]
	v_lshlrev_b64 v[176:177], 13, v[176:177]
	v_lshl_add_u64 v[176:177], v[4:5], 0, v[176:177]
	s_and_b64 exec, exec, vcc
	global_load_dwordx4 v[164:167], v[176:177], off
	s_and_b64 exec, s[2:3], s[20:21]
	v_add_u32_e32 v188, s24, v95
	v_cmp_lt_i32_e32 vcc, -1, v188
	v_mov_b32_e32 v168, 0
	v_mov_b32_e32 v169, 0
	v_mov_b32_e32 v170, 0
	v_mov_b32_e32 v171, 0
	v_lshl_add_u64 v[176:177], s[58:59], 0, v[188:189]
	v_lshlrev_b64 v[176:177], 13, v[176:177]
	v_lshl_add_u64 v[176:177], v[4:5], 0, v[176:177]
	s_and_b64 exec, exec, vcc
	global_load_dwordx4 v[168:171], v[176:177], off
	s_and_b64 exec, s[2:3], s[22:23]
	v_add_u32_e32 v188, s24, v96
	v_cmp_lt_i32_e32 vcc, -1, v188
	v_mov_b32_e32 v172, 0
	v_mov_b32_e32 v173, 0
	v_mov_b32_e32 v174, 0
	v_mov_b32_e32 v175, 0
	v_lshl_add_u64 v[176:177], s[58:59], 0, v[188:189]
	v_lshlrev_b64 v[176:177], 13, v[176:177]
	v_lshl_add_u64 v[176:177], v[4:5], 0, v[176:177]
	s_and_b64 exec, exec, vcc
	global_load_dwordx4 v[172:175], v[176:177], off
	s_mov_b64 exec, s[2:3]
	s_lshl_b32 s98, s29, 10
	s_mov_b32 s99, 0
	v_lshl_add_u64 v[176:177], v[74:75], 0, s[98:99]
	global_load_dwordx4 v[180:183], v[176:177], off
	global_load_dwordx4 v[184:187], v[176:177], off offset:64
	global_load_dwordx4 v[196:199], v[176:177], off offset:128
	global_load_dwordx4 v[200:203], v[176:177], off offset:192
	s_waitcnt vmcnt(4)
	s_and_b64 exec, s[2:3], s[6:7]
	v_add_u32_e32 v6, v70, v73
	ds_write_b128 v6, v[140:143]
	s_and_b64 exec, s[2:3], s[8:9]
	v_add_u32_e32 v6, v70, v89
	ds_write_b128 v6, v[144:147]
	s_and_b64 exec, s[2:3], s[10:11]
	v_add_u32_e32 v6, v70, v89
	ds_write_b128 v6, v[148:151] offset:8448
	s_and_b64 exec, s[2:3], s[12:13]
	v_add_u32_e32 v6, v70, v89
	ds_write_b128 v6, v[152:155] offset:16896
	s_and_b64 exec, s[2:3], s[14:15]
	v_add_u32_e32 v6, v70, v89
	ds_write_b128 v6, v[156:159] offset:25344
	s_and_b64 exec, s[2:3], s[16:17]
	v_add_u32_e32 v6, v70, v89
	ds_write_b128 v6, v[160:163] offset:33792
	s_and_b64 exec, s[2:3], s[18:19]
	v_add_u32_e32 v6, v70, v89
	ds_write_b128 v6, v[164:167] offset:42240
	s_and_b64 exec, s[2:3], s[20:21]
	v_add_u32_e32 v6, v70, v89
	ds_write_b128 v6, v[168:171] offset:50688
	s_and_b64 exec, s[2:3], s[22:23]
	v_add_u32_e32 v6, v70, v89
	ds_write_b128 v6, v[172:175] offset:59136
	s_mov_b64 exec, s[2:3]
	v_or_b32_e32 v0, s64, v66
	v_lshlrev_b32_e32 v188, 2, v0
	global_load_dwordx4 v[16:19], v188, s[54:55] offset:16
	global_load_dwordx4 v[0:3], v188, s[52:53] offset:16
	global_load_dwordx4 v[20:23], v188, s[54:55]
	global_load_dwordx4 v[4:7], v188, s[52:53]
	global_load_dwordx4 v[8:11], v188, s[50:51]
	global_load_dwordx4 v[12:15], v188, s[50:51] offset:16
	s_add_i32 s24, s26, s69
	s_and_b32 s3, s31, 3
	s_waitcnt vmcnt(8)
	v_lshlrev_b32_e32 v24, 1, v66
	s_and_b32 s0, s78, 0xf80
	s_ashr_i32 s25, s24, 31
	s_lshr_b32 s2, s78, 7
	v_lshl_or_b32 v84, s3, 9, v24
	v_add_u32_e32 v34, s0, v64
	v_add_u32_e32 v24, s0, v91
	s_waitcnt vmcnt(7)
	v_add_u32_e32 v26, s0, v90
	v_add_u32_e32 v28, s0, v88
	s_lshl_b64 s[0:1], s[24:25], 13
	s_add_u32 s0, s43, s0
	s_addc_u32 s1, s68, s1
	s_lshl_b64 s[60:61], s[26:27], 24
	v_lshl_add_u64 v[36:37], s[0:1], 0, v[188:189]
	s_add_u32 s0, s74, s60
	s_addc_u32 s1, s75, s61
	s_lshl_b64 s[62:63], s[26:27], 25
	v_ashrrev_i32_e32 v25, 31, v24
	v_ashrrev_i32_e32 v27, 31, v26
	v_ashrrev_i32_e32 v35, 31, v34
	v_ashrrev_i32_e32 v29, 31, v28
	s_add_u32 s26, s38, s62
	s_waitcnt vmcnt(6)
	v_lshlrev_b64 v[30:31], 12, v[24:25]
	v_lshlrev_b64 v[24:25], 13, v[24:25]
	v_lshlrev_b64 v[32:33], 12, v[26:27]
	v_lshlrev_b64 v[48:49], 13, v[34:35]
	v_lshlrev_b64 v[26:27], 13, v[26:27]
	v_lshlrev_b64 v[42:43], 12, v[28:29]
	v_lshlrev_b64 v[28:29], 13, v[28:29]
	v_lshlrev_b64 v[44:45], 12, v[34:35]
	s_addc_u32 s27, s39, s63
	v_mov_b32_e32 v85, v189
	v_lshl_add_u64 v[38:39], s[0:1], 0, v[30:31]
	v_lshl_add_u64 v[40:41], s[0:1], 0, v[32:33]
	v_lshl_add_u64 v[42:43], s[0:1], 0, v[42:43]
	v_lshl_add_u64 v[44:45], s[0:1], 0, v[44:45]
	v_lshl_add_u64 v[46:47], s[26:27], 0, v[24:25]
	v_lshl_add_u64 v[48:49], s[26:27], 0, v[48:49]
	v_lshl_add_u64 v[50:51], s[26:27], 0, v[26:27]
	v_lshl_add_u64 v[52:53], s[26:27], 0, v[28:29]
	s_mov_b32 s25, 0
	s_waitcnt vmcnt(5)
	v_mov_b32_e32 v54, v18
	s_waitcnt vmcnt(4)
	v_mov_b32_e32 v55, v2
	v_mov_b32_e32 v2, v19
	v_mov_b32_e32 v56, v16
	v_mov_b32_e32 v57, v0
	v_mov_b32_e32 v0, v17
	s_waitcnt vmcnt(3)
	v_mov_b32_e32 v58, v22
	s_waitcnt vmcnt(2)
	v_mov_b32_e32 v59, v6
	v_mov_b32_e32 v6, v23
	v_mov_b32_e32 v60, v20
	v_mov_b32_e32 v61, v4
	v_mov_b32_e32 v4, v21
	s_branch .LBB0_386

.LBB0_390:
	s_or_b64 exec, exec, s[0:1]
	v_add_co_u32_e32 v16, vcc, 0x6089000, v16
	s_nop 1
	v_addc_co_u32_e32 v17, vcc, 0, v17, vcc
	global_load_dwordx4 v[106:109], v[16:17], off offset:2816
	s_waitcnt vmcnt(1)
	v_lshlrev_b32_e32 v24, 16, v26
	v_lshlrev_b32_e32 v17, 16, v30
	v_lshlrev_b32_e32 v16, 16, v20
	v_pk_mul_f32 v[18:19], v[60:61], v[16:17]
	v_and_b32_e32 v63, 0xffff0000, v30
	v_fma_f32 v17, v8, v24, v19
	v_and_b32_e32 v62, 0xffff0000, v20
	v_add_f32_e32 v17, v18, v17
	v_and_b32_e32 v24, 0xffff0000, v26
	v_pk_mul_f32 v[18:19], v[4:5], v[62:63]
	v_and_b32_e32 v30, 0xffff0000, v21
	v_fma_f32 v19, v9, v24, v19
	v_add_f32_e32 v18, v18, v19
	v_and_b32_e32 v87, 0xffff0000, v32
	v_and_b32_e32 v86, 0xffff0000, v22
	v_cmp_lt_i32_e32 vcc, s72, v35
	s_waitcnt vmcnt(0)
	v_lshlrev_b32_e32 v19, 16, v106
	v_mul_f32_e32 v17, v17, v19
	v_and_b32_e32 v19, 0xffff0000, v106
	v_mul_f32_e32 v18, v18, v19
	v_cvt_pk_bf16_f32 v20, v17, v18
	v_lshlrev_b32_e32 v19, 16, v31
	v_lshlrev_b32_e32 v18, 16, v21
	v_lshlrev_b32_e32 v17, 16, v27
	v_pk_mul_f32 v[24:25], v[58:59], v[18:19]
	v_and_b32_e32 v31, 0xffff0000, v31
	v_fma_f32 v17, v10, v17, v25
	v_add_f32_e32 v17, v24, v17
	v_and_b32_e32 v19, 0xffff0000, v27
	v_pk_mul_f32 v[24:25], v[6:7], v[30:31]
	v_lshlrev_b32_e32 v21, 16, v107
	v_fma_f32 v19, v11, v19, v25
	v_add_f32_e32 v19, v24, v19
	v_mul_f32_e32 v17, v17, v21
	v_and_b32_e32 v21, 0xffff0000, v107
	v_lshlrev_b32_e32 v25, 16, v32
	v_lshlrev_b32_e32 v24, 16, v22
	v_mul_f32_e32 v19, v19, v21
	v_cvt_pk_bf16_f32 v21, v17, v19
	v_lshlrev_b32_e32 v17, 16, v28
	v_pk_mul_f32 v[26:27], v[56:57], v[24:25]
	v_and_b32_e32 v19, 0xffff0000, v28
	v_fma_f32 v17, v12, v17, v27
	v_add_f32_e32 v17, v26, v17
	v_pk_mul_f32 v[26:27], v[0:1], v[86:87]
	v_lshlrev_b32_e32 v22, 16, v108
	v_fma_f32 v19, v13, v19, v27
	v_add_f32_e32 v19, v26, v19
	v_mul_f32_e32 v17, v17, v22
	v_and_b32_e32 v22, 0xffff0000, v108
	v_mul_f32_e32 v19, v19, v22
	v_lshlrev_b32_e32 v27, 16, v33
	v_lshlrev_b32_e32 v26, 16, v23
	v_cvt_pk_bf16_f32 v22, v17, v19
	v_lshlrev_b32_e32 v17, 16, v29
	v_pk_mul_f32 v[106:107], v[54:55], v[26:27]
	v_and_b32_e32 v19, 0xffff0000, v29
	v_and_b32_e32 v29, 0xffff0000, v33
	v_and_b32_e32 v28, 0xffff0000, v23
	v_fma_f32 v17, v14, v17, v107
	v_pk_mul_f32 v[32:33], v[2:3], v[28:29]
	v_add_f32_e32 v17, v106, v17
	v_fma_f32 v19, v15, v19, v33
	v_lshlrev_b32_e32 v23, 16, v109
	v_add_f32_e32 v19, v32, v19
	v_mul_f32_e32 v17, v17, v23
	v_and_b32_e32 v23, 0xffff0000, v109
	v_lshl_add_u64 v[32:33], v[44:45], 0, v[84:85]
	v_mul_f32_e32 v19, v19, v23
	v_cvt_pk_bf16_f32 v23, v17, v19
	global_store_dwordx4 v[32:33], v[20:23], off
	s_and_saveexec_b64 s[0:1], vcc
	s_cbranch_execz .LBB0_392
	v_add_u32_e32 v188, 0xfffff002, v35
	v_lshlrev_b64 v[20:21], 12, v[188:189]
	v_lshl_add_u64 v[20:21], v[36:37], 0, v[20:21]
	v_mov_b32_e32 v17, v62
	v_mov_b32_e32 v19, v30
	v_mov_b32_e32 v25, v86
	v_mov_b32_e32 v27, v28
	global_store_dwordx4 v[20:21], v[16:19], off
	global_store_dwordx4 v[20:21], v[24:27], off offset:16

.LBB0_396:
	s_or_b64 exec, exec, s[0:1]
	v_add_co_u32_e32 v16, vcc, 0x6089000, v16
	s_nop 1
	v_addc_co_u32_e32 v17, vcc, 0, v17, vcc
	global_load_dwordx4 v[106:109], v[16:17], off offset:2816
	s_waitcnt vmcnt(1)
	v_lshlrev_b32_e32 v24, 16, v26
	v_lshlrev_b32_e32 v17, 16, v30
	v_lshlrev_b32_e32 v16, 16, v20
	v_pk_mul_f32 v[18:19], v[60:61], v[16:17]
	v_and_b32_e32 v63, 0xffff0000, v30
	v_fma_f32 v17, v8, v24, v19
	v_and_b32_e32 v62, 0xffff0000, v20
	v_add_f32_e32 v17, v18, v17
	v_and_b32_e32 v24, 0xffff0000, v26
	v_pk_mul_f32 v[18:19], v[4:5], v[62:63]
	v_and_b32_e32 v30, 0xffff0000, v21
	v_fma_f32 v19, v9, v24, v19
	v_add_f32_e32 v18, v18, v19
	v_and_b32_e32 v87, 0xffff0000, v32
	v_and_b32_e32 v86, 0xffff0000, v22
	v_cmp_lt_i32_e32 vcc, s72, v83
	s_waitcnt vmcnt(0)
	v_lshlrev_b32_e32 v19, 16, v106
	v_mul_f32_e32 v17, v17, v19
	v_and_b32_e32 v19, 0xffff0000, v106
	v_mul_f32_e32 v18, v18, v19
	v_cvt_pk_bf16_f32 v20, v17, v18
	v_lshlrev_b32_e32 v19, 16, v31
	v_lshlrev_b32_e32 v18, 16, v21
	v_lshlrev_b32_e32 v17, 16, v27
	v_pk_mul_f32 v[24:25], v[58:59], v[18:19]
	v_and_b32_e32 v31, 0xffff0000, v31
	v_fma_f32 v17, v10, v17, v25
	v_add_f32_e32 v17, v24, v17
	v_and_b32_e32 v19, 0xffff0000, v27
	v_pk_mul_f32 v[24:25], v[6:7], v[30:31]
	v_lshlrev_b32_e32 v21, 16, v107
	v_fma_f32 v19, v11, v19, v25
	v_add_f32_e32 v19, v24, v19
	v_mul_f32_e32 v17, v17, v21
	v_and_b32_e32 v21, 0xffff0000, v107
	v_lshlrev_b32_e32 v25, 16, v32
	v_lshlrev_b32_e32 v24, 16, v22
	v_mul_f32_e32 v19, v19, v21
	v_cvt_pk_bf16_f32 v21, v17, v19
	v_lshlrev_b32_e32 v17, 16, v28
	v_pk_mul_f32 v[26:27], v[56:57], v[24:25]
	v_and_b32_e32 v19, 0xffff0000, v28
	v_fma_f32 v17, v12, v17, v27
	v_add_f32_e32 v17, v26, v17
	v_pk_mul_f32 v[26:27], v[0:1], v[86:87]
	v_lshlrev_b32_e32 v22, 16, v108
	v_fma_f32 v19, v13, v19, v27
	v_add_f32_e32 v19, v26, v19
	v_mul_f32_e32 v17, v17, v22
	v_and_b32_e32 v22, 0xffff0000, v108
	v_mul_f32_e32 v19, v19, v22
	v_lshlrev_b32_e32 v27, 16, v33
	v_lshlrev_b32_e32 v26, 16, v23
	v_cvt_pk_bf16_f32 v22, v17, v19
	v_lshlrev_b32_e32 v17, 16, v29
	v_pk_mul_f32 v[106:107], v[54:55], v[26:27]
	v_and_b32_e32 v19, 0xffff0000, v29
	v_and_b32_e32 v29, 0xffff0000, v33
	v_and_b32_e32 v28, 0xffff0000, v23
	v_fma_f32 v17, v14, v17, v107
	v_pk_mul_f32 v[32:33], v[2:3], v[28:29]
	v_add_f32_e32 v17, v106, v17
	v_fma_f32 v19, v15, v19, v33
	v_lshlrev_b32_e32 v23, 16, v109
	v_add_f32_e32 v19, v32, v19
	v_mul_f32_e32 v17, v17, v23
	v_and_b32_e32 v23, 0xffff0000, v109
	v_lshl_add_u64 v[32:33], v[42:43], 0, v[84:85]
	v_mul_f32_e32 v19, v19, v23
	v_cvt_pk_bf16_f32 v23, v17, v19
	global_store_dwordx4 v[32:33], v[20:23], off
	s_and_saveexec_b64 s[0:1], vcc
	s_cbranch_execz .LBB0_398
	v_add_u32_e32 v188, 0xfffff012, v35
	v_lshlrev_b64 v[20:21], 12, v[188:189]
	v_lshl_add_u64 v[20:21], v[36:37], 0, v[20:21]
	v_mov_b32_e32 v17, v62
	v_mov_b32_e32 v19, v30
	v_mov_b32_e32 v25, v86
	v_mov_b32_e32 v27, v28
	global_store_dwordx4 v[20:21], v[16:19], off
	global_store_dwordx4 v[20:21], v[24:27], off offset:16

.LBB0_402:
	s_or_b64 exec, exec, s[0:1]
	v_add_co_u32_e32 v16, vcc, 0x6089000, v16
	s_nop 1
	v_addc_co_u32_e32 v17, vcc, 0, v17, vcc
	global_load_dwordx4 v[106:109], v[16:17], off offset:2816
	s_waitcnt vmcnt(1)
	v_lshlrev_b32_e32 v24, 16, v26
	v_lshlrev_b32_e32 v17, 16, v30
	v_lshlrev_b32_e32 v16, 16, v20
	v_pk_mul_f32 v[18:19], v[60:61], v[16:17]
	v_and_b32_e32 v63, 0xffff0000, v30
	v_fma_f32 v17, v8, v24, v19
	v_and_b32_e32 v62, 0xffff0000, v20
	v_add_f32_e32 v17, v18, v17
	v_and_b32_e32 v24, 0xffff0000, v26
	v_pk_mul_f32 v[18:19], v[4:5], v[62:63]
	v_and_b32_e32 v30, 0xffff0000, v21
	v_fma_f32 v19, v9, v24, v19
	v_add_f32_e32 v18, v18, v19
	v_and_b32_e32 v87, 0xffff0000, v32
	v_and_b32_e32 v86, 0xffff0000, v22
	v_cmp_lt_i32_e32 vcc, s72, v83
	s_waitcnt vmcnt(0)
	v_lshlrev_b32_e32 v19, 16, v106
	v_mul_f32_e32 v17, v17, v19
	v_and_b32_e32 v19, 0xffff0000, v106
	v_mul_f32_e32 v18, v18, v19
	v_cvt_pk_bf16_f32 v20, v17, v18
	v_lshlrev_b32_e32 v19, 16, v31
	v_lshlrev_b32_e32 v18, 16, v21
	v_lshlrev_b32_e32 v17, 16, v27
	v_pk_mul_f32 v[24:25], v[58:59], v[18:19]
	v_and_b32_e32 v31, 0xffff0000, v31
	v_fma_f32 v17, v10, v17, v25
	v_add_f32_e32 v17, v24, v17
	v_and_b32_e32 v19, 0xffff0000, v27
	v_pk_mul_f32 v[24:25], v[6:7], v[30:31]
	v_lshlrev_b32_e32 v21, 16, v107
	v_fma_f32 v19, v11, v19, v25
	v_add_f32_e32 v19, v24, v19
	v_mul_f32_e32 v17, v17, v21
	v_and_b32_e32 v21, 0xffff0000, v107
	v_lshlrev_b32_e32 v25, 16, v32
	v_lshlrev_b32_e32 v24, 16, v22
	v_mul_f32_e32 v19, v19, v21
	v_cvt_pk_bf16_f32 v21, v17, v19
	v_lshlrev_b32_e32 v17, 16, v28
	v_pk_mul_f32 v[26:27], v[56:57], v[24:25]
	v_and_b32_e32 v19, 0xffff0000, v28
	v_fma_f32 v17, v12, v17, v27
	v_add_f32_e32 v17, v26, v17
	v_pk_mul_f32 v[26:27], v[0:1], v[86:87]
	v_lshlrev_b32_e32 v22, 16, v108
	v_fma_f32 v19, v13, v19, v27
	v_add_f32_e32 v19, v26, v19
	v_mul_f32_e32 v17, v17, v22
	v_and_b32_e32 v22, 0xffff0000, v108
	v_mul_f32_e32 v19, v19, v22
	v_lshlrev_b32_e32 v27, 16, v33
	v_lshlrev_b32_e32 v26, 16, v23
	v_cvt_pk_bf16_f32 v22, v17, v19
	v_lshlrev_b32_e32 v17, 16, v29
	v_pk_mul_f32 v[106:107], v[54:55], v[26:27]
	v_and_b32_e32 v19, 0xffff0000, v29
	v_and_b32_e32 v29, 0xffff0000, v33
	v_and_b32_e32 v28, 0xffff0000, v23
	v_fma_f32 v17, v14, v17, v107
	v_pk_mul_f32 v[32:33], v[2:3], v[28:29]
	v_add_f32_e32 v17, v106, v17
	v_fma_f32 v19, v15, v19, v33
	v_lshlrev_b32_e32 v23, 16, v109
	v_add_f32_e32 v19, v32, v19
	v_mul_f32_e32 v17, v17, v23
	v_and_b32_e32 v23, 0xffff0000, v109
	v_lshl_add_u64 v[32:33], v[40:41], 0, v[84:85]
	v_mul_f32_e32 v19, v19, v23
	v_cvt_pk_bf16_f32 v23, v17, v19
	global_store_dwordx4 v[32:33], v[20:23], off
	s_and_saveexec_b64 s[0:1], vcc
	s_cbranch_execz .LBB0_404
	v_add_u32_e32 v188, 0xfffff022, v35
	v_lshlrev_b64 v[20:21], 12, v[188:189]
	v_lshl_add_u64 v[20:21], v[36:37], 0, v[20:21]
	v_mov_b32_e32 v17, v62
	v_mov_b32_e32 v19, v30
	v_mov_b32_e32 v25, v86
	v_mov_b32_e32 v27, v28
	global_store_dwordx4 v[20:21], v[16:19], off
	global_store_dwordx4 v[20:21], v[24:27], off offset:16

.LBB0_408:
	s_or_b64 exec, exec, s[0:1]
	v_add_co_u32_e32 v16, vcc, 0x6089000, v16
	s_nop 1
	v_addc_co_u32_e32 v17, vcc, 0, v17, vcc
	global_load_dwordx4 v[106:109], v[16:17], off offset:2816
	s_waitcnt vmcnt(1)
	v_lshlrev_b32_e32 v24, 16, v26
	v_lshlrev_b32_e32 v17, 16, v30
	v_lshlrev_b32_e32 v16, 16, v20
	v_pk_mul_f32 v[18:19], v[60:61], v[16:17]
	v_and_b32_e32 v63, 0xffff0000, v30
	v_fma_f32 v17, v8, v24, v19
	v_and_b32_e32 v62, 0xffff0000, v20
	v_add_f32_e32 v17, v18, v17
	v_and_b32_e32 v24, 0xffff0000, v26
	v_pk_mul_f32 v[18:19], v[4:5], v[62:63]
	v_and_b32_e32 v30, 0xffff0000, v21
	v_fma_f32 v19, v9, v24, v19
	v_add_f32_e32 v18, v18, v19
	v_and_b32_e32 v87, 0xffff0000, v32
	v_and_b32_e32 v86, 0xffff0000, v22
	v_cmp_lt_i32_e32 vcc, s72, v83
	s_waitcnt vmcnt(0)
	v_lshlrev_b32_e32 v19, 16, v106
	v_mul_f32_e32 v17, v17, v19
	v_and_b32_e32 v19, 0xffff0000, v106
	v_mul_f32_e32 v18, v18, v19
	v_cvt_pk_bf16_f32 v20, v17, v18
	v_lshlrev_b32_e32 v19, 16, v31
	v_lshlrev_b32_e32 v18, 16, v21
	v_lshlrev_b32_e32 v17, 16, v27
	v_pk_mul_f32 v[24:25], v[58:59], v[18:19]
	v_and_b32_e32 v31, 0xffff0000, v31
	v_fma_f32 v17, v10, v17, v25
	v_add_f32_e32 v17, v24, v17
	v_and_b32_e32 v19, 0xffff0000, v27
	v_pk_mul_f32 v[24:25], v[6:7], v[30:31]
	v_lshlrev_b32_e32 v21, 16, v107
	v_fma_f32 v19, v11, v19, v25
	v_add_f32_e32 v19, v24, v19
	v_mul_f32_e32 v17, v17, v21
	v_and_b32_e32 v21, 0xffff0000, v107
	v_lshlrev_b32_e32 v25, 16, v32
	v_lshlrev_b32_e32 v24, 16, v22
	v_mul_f32_e32 v19, v19, v21
	v_cvt_pk_bf16_f32 v21, v17, v19
	v_lshlrev_b32_e32 v17, 16, v28
	v_pk_mul_f32 v[26:27], v[56:57], v[24:25]
	v_and_b32_e32 v19, 0xffff0000, v28
	v_fma_f32 v17, v12, v17, v27
	v_add_f32_e32 v17, v26, v17
	v_pk_mul_f32 v[26:27], v[0:1], v[86:87]
	v_lshlrev_b32_e32 v22, 16, v108
	v_fma_f32 v19, v13, v19, v27
	v_add_f32_e32 v19, v26, v19
	v_mul_f32_e32 v17, v17, v22
	v_and_b32_e32 v22, 0xffff0000, v108
	v_mul_f32_e32 v19, v19, v22
	v_lshlrev_b32_e32 v27, 16, v33
	v_lshlrev_b32_e32 v26, 16, v23
	v_cvt_pk_bf16_f32 v22, v17, v19
	v_lshlrev_b32_e32 v17, 16, v29
	v_pk_mul_f32 v[106:107], v[54:55], v[26:27]
	v_and_b32_e32 v19, 0xffff0000, v29
	v_and_b32_e32 v29, 0xffff0000, v33
	v_and_b32_e32 v28, 0xffff0000, v23
	v_fma_f32 v17, v14, v17, v107
	v_pk_mul_f32 v[32:33], v[2:3], v[28:29]
	v_add_f32_e32 v17, v106, v17
	v_fma_f32 v19, v15, v19, v33
	v_lshlrev_b32_e32 v23, 16, v109
	v_add_f32_e32 v19, v32, v19
	v_mul_f32_e32 v17, v17, v23
	v_and_b32_e32 v23, 0xffff0000, v109
	v_lshl_add_u64 v[32:33], v[38:39], 0, v[84:85]
	v_mul_f32_e32 v19, v19, v23
	v_cvt_pk_bf16_f32 v23, v17, v19
	global_store_dwordx4 v[32:33], v[20:23], off
	s_and_saveexec_b64 s[0:1], vcc
	s_cbranch_execz .LBB0_385
	v_add_u32_e32 v188, 0xfffff032, v35
	v_lshlrev_b64 v[20:21], 12, v[188:189]
	v_lshl_add_u64 v[20:21], v[36:37], 0, v[20:21]
	v_mov_b32_e32 v17, v62
	v_mov_b32_e32 v19, v30
	v_mov_b32_e32 v25, v86
	v_mov_b32_e32 v27, v28
	global_store_dwordx4 v[20:21], v[16:19], off
	global_store_dwordx4 v[20:21], v[24:27], off offset:16
	s_branch .LBB0_385

.LBB0_421:
	v_lshl_add_u64 v[110:111], v[86:87], 0, s[66:67]
	s_mov_b32 s0, 0x1f2a8000
	v_add_co_u32_e32 v126, vcc, s0, v110
	s_mov_b32 s0, 0x1f2aa000
	v_add_co_u32_e64 v128, s[24:25], s0, v110
	s_mov_b32 s0, 0x1f2ac000
	v_add_co_u32_e64 v130, s[26:27], s0, v110
	s_mov_b32 s0, 0x1f2ae000
	v_add_co_u32_e64 v132, s[28:29], s0, v110
	v_addc_co_u32_e32 v127, vcc, 0, v111, vcc
	v_addc_co_u32_e64 v129, vcc, 0, v111, s[24:25]
	v_addc_co_u32_e64 v131, vcc, 0, v111, s[26:27]
	v_addc_co_u32_e64 v133, vcc, 0, v111, s[28:29]
	global_load_dwordx4 v[110:113], v[126:127], off offset:768
	global_load_dwordx4 v[114:117], v[128:129], off offset:768
	global_load_dwordx4 v[118:121], v[130:131], off offset:768
	global_load_dwordx4 v[122:125], v[132:133], off offset:768
	ds_read_b128 v[106:109], v83
	s_add_u32 s66, s66, 0x80
	s_addc_u32 s67, s67, 0
	s_cmpk_eq_i32 s66, 0x200
	s_waitcnt vmcnt(3) lgkmcnt(0)
	v_mfma_f32_16x16x32_bf16 v[48:51], v[110:113], v[106:109], v[48:51]
	s_waitcnt vmcnt(2)
	v_mfma_f32_16x16x32_bf16 v[60:63], v[114:117], v[106:109], v[60:63]
	s_waitcnt vmcnt(1)
	v_mfma_f32_16x16x32_bf16 v[56:59], v[118:121], v[106:109], v[56:59]
	s_waitcnt vmcnt(0)
	v_mfma_f32_16x16x32_bf16 v[52:55], v[122:125], v[106:109], v[52:55]
	ds_read_b128 v[106:109], v83 offset:8448
	s_waitcnt lgkmcnt(0)
	v_mfma_f32_16x16x32_bf16 v[44:47], v[110:113], v[106:109], v[44:47]
	v_mfma_f32_16x16x32_bf16 v[40:43], v[114:117], v[106:109], v[40:43]
	v_mfma_f32_16x16x32_bf16 v[36:39], v[118:121], v[106:109], v[36:39]
	v_mfma_f32_16x16x32_bf16 v[24:27], v[122:125], v[106:109], v[24:27]
	ds_read_b128 v[106:109], v83 offset:16896
	s_waitcnt lgkmcnt(0)
	v_mfma_f32_16x16x32_bf16 v[32:35], v[110:113], v[106:109], v[32:35]
	v_mfma_f32_16x16x32_bf16 v[20:23], v[114:117], v[106:109], v[20:23]
	v_mfma_f32_16x16x32_bf16 v[12:15], v[118:121], v[106:109], v[12:15]
	v_mfma_f32_16x16x32_bf16 v[4:7], v[122:125], v[106:109], v[4:7]
	ds_read_b128 v[106:109], v83 offset:25344
	s_waitcnt lgkmcnt(0)
	v_mfma_f32_16x16x32_bf16 v[28:31], v[110:113], v[106:109], v[28:31]
	ds_read_b128 v[110:113], v83 offset:64
	v_mfma_f32_16x16x32_bf16 v[16:19], v[114:117], v[106:109], v[16:19]
	global_load_dwordx4 v[114:117], v[128:129], off offset:832
	v_mfma_f32_16x16x32_bf16 v[8:11], v[118:121], v[106:109], v[8:11]
	global_load_dwordx4 v[118:121], v[130:131], off offset:832
	v_mfma_f32_16x16x32_bf16 v[0:3], v[122:125], v[106:109], v[0:3]
	global_load_dwordx4 v[106:109], v[126:127], off offset:832
	global_load_dwordx4 v[122:125], v[132:133], off offset:832
	s_waitcnt vmcnt(1) lgkmcnt(0)
	v_mfma_f32_16x16x32_bf16 v[48:51], v[106:109], v[110:113], v[48:51]
	v_mfma_f32_16x16x32_bf16 v[60:63], v[114:117], v[110:113], v[60:63]
	v_mfma_f32_16x16x32_bf16 v[56:59], v[118:121], v[110:113], v[56:59]
	s_waitcnt vmcnt(0)
	v_mfma_f32_16x16x32_bf16 v[52:55], v[122:125], v[110:113], v[52:55]
	ds_read_b128 v[110:113], v83 offset:8512
	s_waitcnt lgkmcnt(0)
	v_mfma_f32_16x16x32_bf16 v[44:47], v[106:109], v[110:113], v[44:47]
	v_mfma_f32_16x16x32_bf16 v[40:43], v[114:117], v[110:113], v[40:43]
	v_mfma_f32_16x16x32_bf16 v[36:39], v[118:121], v[110:113], v[36:39]
	v_mfma_f32_16x16x32_bf16 v[24:27], v[122:125], v[110:113], v[24:27]
	ds_read_b128 v[110:113], v83 offset:16960
	s_waitcnt lgkmcnt(0)
	v_mfma_f32_16x16x32_bf16 v[32:35], v[106:109], v[110:113], v[32:35]
	v_mfma_f32_16x16x32_bf16 v[20:23], v[114:117], v[110:113], v[20:23]
	v_mfma_f32_16x16x32_bf16 v[12:15], v[118:121], v[110:113], v[12:15]
	v_mfma_f32_16x16x32_bf16 v[4:7], v[122:125], v[110:113], v[4:7]
	ds_read_b128 v[110:113], v83 offset:25408
	v_add_u32_e32 v83, 0x80, v83
	s_waitcnt lgkmcnt(0)
	v_mfma_f32_16x16x32_bf16 v[28:31], v[106:109], v[110:113], v[28:31]
	v_mfma_f32_16x16x32_bf16 v[16:19], v[114:117], v[110:113], v[16:19]
	v_mfma_f32_16x16x32_bf16 v[8:11], v[118:121], v[110:113], v[8:11]
	v_mfma_f32_16x16x32_bf16 v[0:3], v[122:125], v[110:113], v[0:3]
	s_cbranch_scc0 .LBB0_421
	s_mov_b32 s65, s85
	v_lshl_add_u64 v[86:87], v[74:75], 0, s[64:65]
	v_add_u32_e32 v83, v97, v98
	s_and_b32 s0, s2, 31
	s_lshl_b32 s1, s0, 19
	s_lshl_b32 s2, s0, 20
	s_lshl_b32 s3, s0, 7
	s_add_u32 s0, s60, s1
	s_addc_u32 s1, s61, 0
	s_waitcnt vmcnt(0)
	v_pk_mul_f32 v[50:51], v[50:51], v[182:183]
	v_pk_mul_f32 v[48:49], v[48:49], v[180:181]
	s_nop 0
	v_cvt_pk_bf16_f32 v106, v48, v49
	v_cvt_pk_bf16_f32 v107, v50, v51
	ds_write_b64 v83, v[106:107]
	v_pk_mul_f32 v[50:51], v[62:63], v[186:187]
	v_pk_mul_f32 v[48:49], v[60:61], v[184:185]
	s_nop 0
	v_cvt_pk_bf16_f32 v60, v48, v49
	v_cvt_pk_bf16_f32 v61, v50, v51
	ds_write_b64 v103, v[60:61]
	v_pk_mul_f32 v[50:51], v[58:59], v[198:199]
	v_pk_mul_f32 v[48:49], v[56:57], v[196:197]
	s_nop 0
	v_cvt_pk_bf16_f32 v56, v48, v49
	v_cvt_pk_bf16_f32 v57, v50, v51
	ds_write_b64 v104, v[56:57]
	v_pk_mul_f32 v[50:51], v[54:55], v[202:203]
	v_pk_mul_f32 v[48:49], v[52:53], v[200:201]
	s_nop 0
	v_cvt_pk_bf16_f32 v52, v48, v49
	v_cvt_pk_bf16_f32 v53, v50, v51
	ds_write_b64 v105, v[52:53]
	v_pk_mul_f32 v[46:47], v[46:47], v[182:183]
	v_pk_mul_f32 v[44:45], v[44:45], v[180:181]
	s_nop 0
	v_cvt_pk_bf16_f32 v48, v44, v45
	v_cvt_pk_bf16_f32 v49, v46, v47
	ds_write_b64 v83, v[48:49] offset:8448
	v_pk_mul_f32 v[42:43], v[42:43], v[186:187]
	v_pk_mul_f32 v[40:41], v[40:41], v[184:185]
	s_nop 0
	v_cvt_pk_bf16_f32 v44, v40, v41
	v_cvt_pk_bf16_f32 v45, v42, v43
	ds_write_b64 v103, v[44:45] offset:8448
	v_pk_mul_f32 v[38:39], v[38:39], v[198:199]
	v_pk_mul_f32 v[36:37], v[36:37], v[196:197]
	s_nop 0
	v_cvt_pk_bf16_f32 v40, v36, v37
	v_cvt_pk_bf16_f32 v41, v38, v39
	ds_write_b64 v104, v[40:41] offset:8448
	v_pk_mul_f32 v[26:27], v[26:27], v[202:203]
	v_pk_mul_f32 v[24:25], v[24:25], v[200:201]
	s_nop 0
	v_cvt_pk_bf16_f32 v36, v24, v25
	v_cvt_pk_bf16_f32 v37, v26, v27
	ds_write_b64 v105, v[36:37] offset:8448
	v_pk_mul_f32 v[26:27], v[34:35], v[182:183]
	v_pk_mul_f32 v[24:25], v[32:33], v[180:181]
	s_nop 0
	v_cvt_pk_bf16_f32 v32, v24, v25
	v_cvt_pk_bf16_f32 v33, v26, v27
	ds_write_b64 v83, v[32:33] offset:16896
	v_pk_mul_f32 v[22:23], v[22:23], v[186:187]
	v_pk_mul_f32 v[20:21], v[20:21], v[184:185]
	s_nop 0
	v_cvt_pk_bf16_f32 v24, v20, v21
	v_cvt_pk_bf16_f32 v25, v22, v23
	ds_write_b64 v103, v[24:25] offset:16896
	v_pk_mul_f32 v[14:15], v[14:15], v[198:199]
	v_pk_mul_f32 v[12:13], v[12:13], v[196:197]
	s_nop 0
	v_cvt_pk_bf16_f32 v20, v12, v13
	v_cvt_pk_bf16_f32 v21, v14, v15
	ds_write_b64 v104, v[20:21] offset:16896
	v_pk_mul_f32 v[6:7], v[6:7], v[202:203]
	v_pk_mul_f32 v[4:5], v[4:5], v[200:201]
	s_nop 0
	v_cvt_pk_bf16_f32 v12, v4, v5
	v_cvt_pk_bf16_f32 v13, v6, v7
	ds_write_b64 v105, v[12:13] offset:16896
	v_pk_mul_f32 v[6:7], v[30:31], v[182:183]
	v_pk_mul_f32 v[4:5], v[28:29], v[180:181]
	s_nop 0
	v_cvt_pk_bf16_f32 v12, v4, v5
	v_cvt_pk_bf16_f32 v13, v6, v7
	ds_write_b64 v83, v[12:13] offset:25344
	v_pk_mul_f32 v[6:7], v[18:19], v[186:187]
	v_pk_mul_f32 v[4:5], v[16:17], v[184:185]
	s_nop 0
	v_cvt_pk_bf16_f32 v12, v4, v5
	v_cvt_pk_bf16_f32 v13, v6, v7
	ds_write_b64 v103, v[12:13] offset:25344
	v_pk_mul_f32 v[6:7], v[10:11], v[198:199]
	v_pk_mul_f32 v[4:5], v[8:9], v[196:197]
	s_nop 0
	v_cvt_pk_bf16_f32 v16, v4, v5
	v_cvt_pk_bf16_f32 v17, v6, v7
	v_lshl_add_u64 v[4:5], v[78:79], 0, s[0:1]
	s_add_u32 s0, s62, s2
	s_addc_u32 s1, s63, 0
	v_lshl_add_u64 v[6:7], v[80:81], 0, s[0:1]
	s_add_u32 s0, s3, s58
	s_addc_u32 s1, 0, s59
	v_lshl_add_u64 v[8:9], s[0:1], 0, v[64:65]
	v_lshlrev_b64 v[10:11], 12, v[8:9]
	v_lshlrev_b64 v[18:19], 13, v[8:9]
	v_lshl_add_u64 v[8:9], s[46:47], 0, v[10:11]
	v_lshl_add_u64 v[10:11], s[56:57], 0, v[18:19]
	s_mov_b32 s0, 0
	ds_write_b64 v104, v[16:17] offset:25344
	v_pk_mul_f32 v[0:1], v[0:1], v[200:201]
	v_pk_mul_f32 v[2:3], v[2:3], v[202:203]
	v_cvt_pk_bf16_f32 v0, v0, v1
	s_nop 0
	v_cvt_pk_bf16_f32 v1, v2, v3
	ds_write_b64 v105, v[0:1] offset:25344
	s_waitcnt lgkmcnt(0)
	s_barrier

.LBB0_486:
	s_or_b64 exec, exec, s[8:9]
	s_mov_b64 s[0:1], exec
	v_mbcnt_lo_u32_b32 v0, s0, 0
	v_mbcnt_hi_u32_b32 v0, s1, v0
	v_cmp_eq_u32_e32 vcc, 0, v0
	s_and_saveexec_b64 s[8:9], vcc
	s_cbranch_execz .LBB0_488
	s_bcnt1_i32_b64 s0, s[0:1]
	v_mov_b32_e32 v0, s0
	global_atomic_add v253, v0, s[2:3] offset:1024
.LBB0_488:
	s_or_b64 exec, exec, s[8:9]
	buffer_inv sc1
	s_waitcnt vmcnt(0)
